# grid-barrier waits busy-poll the arrival counter (no s_sleep between polls)
# baseline (speedup 1.0000x reference)
.LBB0_18:
	s_nop 0
	global_load_dword v2, v0, s[4:5] offset:32 sc1
	s_waitcnt vmcnt(0)
	v_and_b32_e32 v2, 0xffff0000, v2
	v_cmp_ne_u32_e32 vcc, v2, v1
	s_or_b64 s[6:7], vcc, s[6:7]
	s_andn2_b64 exec, exec, s[6:7]
	s_cbranch_execnz .LBB0_18

.LBB0_84:
	global_load_dword v15, v16, s[78:79] offset:1024 sc1
	s_waitcnt lgkmcnt(0)
	global_load_dword v0, v16, s[78:79] offset:1280 sc1
	global_load_dword v1, v16, s[78:79] offset:1536 sc1
	global_load_dword v2, v16, s[78:79] offset:1792 sc1
	global_load_dword v3, v16, s[78:79] offset:2048 sc1
	global_load_dword v4, v16, s[78:79] offset:2304 sc1
	global_load_dword v5, v16, s[78:79] offset:2560 sc1
	global_load_dword v6, v16, s[78:79] offset:2816 sc1
	global_load_dword v7, v16, s[78:79] offset:3072 sc1
	global_load_dword v8, v16, s[78:79] offset:3328 sc1
	global_load_dword v9, v16, s[78:79] offset:3584 sc1
	global_load_dword v10, v16, s[78:79] offset:3840 sc1
	global_load_dword v11, v16, s[6:7] sc1
	global_load_dword v12, v16, s[8:9] sc1
	global_load_dword v13, v16, s[10:11] sc1
	global_load_dword v14, v16, s[12:13] sc1
	s_mov_b64 s[14:15], -1
	s_mov_b64 s[16:17], -1
	s_waitcnt vmcnt(14)
	v_add_u32_e32 v17, v0, v15
	s_waitcnt vmcnt(13)
	v_add_u32_e32 v17, v17, v1
	s_waitcnt vmcnt(12)
	v_add_u32_e32 v17, v17, v2
	s_waitcnt vmcnt(11)
	v_add_u32_e32 v17, v17, v3
	s_waitcnt vmcnt(10)
	v_add_u32_e32 v17, v17, v4
	s_waitcnt vmcnt(9)
	v_add_u32_e32 v17, v17, v5
	s_waitcnt vmcnt(8)
	v_add_u32_e32 v17, v17, v6
	s_waitcnt vmcnt(7)
	v_add_u32_e32 v17, v17, v7
	s_waitcnt vmcnt(6)
	v_add_u32_e32 v17, v17, v8
	s_waitcnt vmcnt(5)
	v_add_u32_e32 v17, v17, v9
	s_waitcnt vmcnt(4)
	v_add_u32_e32 v17, v17, v10
	s_waitcnt vmcnt(3)
	v_add_u32_e32 v17, v17, v11
	s_waitcnt vmcnt(2)
	v_add_u32_e32 v17, v17, v12
	s_waitcnt vmcnt(1)
	v_add_u32_e32 v17, v17, v13
	s_waitcnt vmcnt(0)
	v_add_u32_e32 v17, v17, v14
	v_cmp_eq_u32_e32 vcc, s3, v17
	s_cbranch_vccnz .LBB0_83
	s_and_b32 s14, s20, 0xff
	s_cmp_eq_u32 s14, 0
	s_mov_b64 s[14:15], -1
	s_mov_b64 s[18:19], -1
	s_nop 0
	s_cbranch_scc0 .LBB0_88
	global_load_dword v17, v16, s[78:79] offset:512 sc1
	s_waitcnt vmcnt(0)
	v_cmp_eq_u32_e32 vcc, 0, v17
	s_cbranch_vccnz .LBB0_90
	s_mov_b64 s[18:19], 0

.LBB0_102:
	s_and_b32 s20, s3, 0xff
	s_mov_b64 s[18:19], -1
	s_cmp_lg_u32 s20, 0
	s_mov_b64 s[22:23], -1
	s_nop 0
	s_cbranch_scc1 .LBB0_105
	global_load_dword v2, v0, s[78:79] offset:512 sc1
	s_waitcnt vmcnt(0)
	v_cmp_eq_u32_e32 vcc, 0, v2
	s_cbranch_vccnz .LBB0_107
	s_mov_b64 s[22:23], 0
	s_mov_b64 s[20:21], -1

.LBB0_119:
	s_and_b32 s20, s3, 0xff
	s_cmp_lg_u32 s20, 0
	s_mov_b64 s[22:23], -1
	s_nop 0
	s_cbranch_scc1 .LBB0_122
	global_load_dword v1, v0, s[12:13] sc1
	s_waitcnt vmcnt(0)
	v_cmp_eq_u32_e32 vcc, 0, v1
	s_cbranch_vccnz .LBB0_124
	s_mov_b64 s[22:23], 0
	s_mov_b64 s[20:21], -1

.LBB0_157:
	global_load_dword v15, v16, s[78:79] offset:1024 sc1
	s_waitcnt lgkmcnt(0)
	global_load_dword v0, v16, s[78:79] offset:1280 sc1
	global_load_dword v1, v16, s[78:79] offset:1536 sc1
	global_load_dword v2, v16, s[78:79] offset:1792 sc1
	global_load_dword v3, v16, s[78:79] offset:2048 sc1
	global_load_dword v4, v16, s[78:79] offset:2304 sc1
	global_load_dword v5, v16, s[78:79] offset:2560 sc1
	global_load_dword v6, v16, s[78:79] offset:2816 sc1
	global_load_dword v7, v16, s[78:79] offset:3072 sc1
	global_load_dword v8, v16, s[78:79] offset:3328 sc1
	global_load_dword v9, v16, s[78:79] offset:3584 sc1
	global_load_dword v10, v16, s[78:79] offset:3840 sc1
	global_load_dword v11, v16, s[4:5] sc1
	global_load_dword v12, v16, s[6:7] sc1
	global_load_dword v13, v16, s[8:9] sc1
	global_load_dword v14, v16, s[10:11] sc1
	s_mov_b64 s[12:13], -1
	s_mov_b64 s[14:15], -1
	s_waitcnt vmcnt(14)
	v_add_u32_e32 v17, v0, v15
	s_waitcnt vmcnt(13)
	v_add_u32_e32 v17, v17, v1
	s_waitcnt vmcnt(12)
	v_add_u32_e32 v17, v17, v2
	s_waitcnt vmcnt(11)
	v_add_u32_e32 v17, v17, v3
	s_waitcnt vmcnt(10)
	v_add_u32_e32 v17, v17, v4
	s_waitcnt vmcnt(9)
	v_add_u32_e32 v17, v17, v5
	s_waitcnt vmcnt(8)
	v_add_u32_e32 v17, v17, v6
	s_waitcnt vmcnt(7)
	v_add_u32_e32 v17, v17, v7
	s_waitcnt vmcnt(6)
	v_add_u32_e32 v17, v17, v8
	s_waitcnt vmcnt(5)
	v_add_u32_e32 v17, v17, v9
	s_waitcnt vmcnt(4)
	v_add_u32_e32 v17, v17, v10
	s_waitcnt vmcnt(3)
	v_add_u32_e32 v17, v17, v11
	s_waitcnt vmcnt(2)
	v_add_u32_e32 v17, v17, v12
	s_waitcnt vmcnt(1)
	v_add_u32_e32 v17, v17, v13
	s_waitcnt vmcnt(0)
	v_add_u32_e32 v17, v17, v14
	v_cmp_eq_u32_e32 vcc, s18, v17
	s_cbranch_vccnz .LBB0_156
	s_and_b32 s12, s19, 0xff
	s_cmp_eq_u32 s12, 0
	s_mov_b64 s[12:13], -1
	s_mov_b64 s[16:17], -1
	s_nop 0
	s_cbranch_scc0 .LBB0_161
	global_load_dword v17, v16, s[78:79] offset:512 sc1
	s_waitcnt vmcnt(0)
	v_cmp_eq_u32_e32 vcc, 0, v17
	s_cbranch_vccnz .LBB0_163
	s_mov_b64 s[16:17], 0

.LBB0_175:
	s_and_b32 s18, s22, 0xff
	s_mov_b64 s[16:17], -1
	s_cmp_lg_u32 s18, 0
	s_mov_b64 s[20:21], -1
	s_nop 0
	s_cbranch_scc1 .LBB0_178
	global_load_dword v2, v0, s[78:79] offset:512 sc1
	s_waitcnt vmcnt(0)
	v_cmp_eq_u32_e32 vcc, 0, v2
	s_cbranch_vccnz .LBB0_180
	s_mov_b64 s[20:21], 0
	s_mov_b64 s[18:19], -1

.LBB0_192:
	s_and_b32 s18, s26, 0xff
	s_cmp_lg_u32 s18, 0
	s_mov_b64 s[20:21], -1
	s_nop 0
	s_cbranch_scc1 .LBB0_195
	global_load_dword v1, v0, s[10:11] sc1
	s_waitcnt vmcnt(0)
	v_cmp_eq_u32_e32 vcc, 0, v1
	s_cbranch_vccnz .LBB0_197
	s_mov_b64 s[20:21], 0
	s_mov_b64 s[18:19], -1

.LBB0_505:
	s_and_b32 s18, s24, 0xff
	s_cmp_lg_u32 s18, 0
	s_mov_b64 s[20:21], -1
	s_nop 0
	s_cbranch_scc1 .LBB0_508
	global_load_dword v1, v0, s[10:11] sc1
	s_waitcnt vmcnt(0)
	v_cmp_eq_u32_e32 vcc, 0, v1
	s_cbranch_vccnz .LBB0_510
	s_mov_b64 s[20:21], 0
	s_mov_b64 s[18:19], -1

.LBB0_1272:
	global_load_dword v15, v16, s[78:79] offset:1024 sc1
	s_waitcnt lgkmcnt(0)
	global_load_dword v0, v16, s[78:79] offset:1280 sc1
	global_load_dword v1, v16, s[78:79] offset:1536 sc1
	global_load_dword v2, v16, s[78:79] offset:1792 sc1
	global_load_dword v3, v16, s[78:79] offset:2048 sc1
	global_load_dword v4, v16, s[78:79] offset:2304 sc1
	global_load_dword v5, v16, s[78:79] offset:2560 sc1
	global_load_dword v6, v16, s[78:79] offset:2816 sc1
	global_load_dword v7, v16, s[78:79] offset:3072 sc1
	global_load_dword v8, v16, s[78:79] offset:3328 sc1
	global_load_dword v9, v16, s[78:79] offset:3584 sc1
	global_load_dword v10, v16, s[78:79] offset:3840 sc1
	global_load_dword v11, v16, s[6:7] sc1
	global_load_dword v12, v16, s[8:9] sc1
	global_load_dword v13, v16, s[10:11] sc1
	global_load_dword v14, v16, s[12:13] sc1
	s_mov_b64 s[14:15], -1
	s_mov_b64 s[16:17], -1
	s_waitcnt vmcnt(14)
	v_add_u32_e32 v17, v0, v15
	s_waitcnt vmcnt(13)
	v_add_u32_e32 v17, v17, v1
	s_waitcnt vmcnt(12)
	v_add_u32_e32 v17, v17, v2
	s_waitcnt vmcnt(11)
	v_add_u32_e32 v17, v17, v3
	s_waitcnt vmcnt(10)
	v_add_u32_e32 v17, v17, v4
	s_waitcnt vmcnt(9)
	v_add_u32_e32 v17, v17, v5
	s_waitcnt vmcnt(8)
	v_add_u32_e32 v17, v17, v6
	s_waitcnt vmcnt(7)
	v_add_u32_e32 v17, v17, v7
	s_waitcnt vmcnt(6)
	v_add_u32_e32 v17, v17, v8
	s_waitcnt vmcnt(5)
	v_add_u32_e32 v17, v17, v9
	s_waitcnt vmcnt(4)
	v_add_u32_e32 v17, v17, v10
	s_waitcnt vmcnt(3)
	v_add_u32_e32 v17, v17, v11
	s_waitcnt vmcnt(2)
	v_add_u32_e32 v17, v17, v12
	s_waitcnt vmcnt(1)
	v_add_u32_e32 v17, v17, v13
	s_waitcnt vmcnt(0)
	v_add_u32_e32 v17, v17, v14
	v_cmp_eq_u32_e32 vcc, s20, v17
	s_cbranch_vccnz .LBB0_1271
	s_and_b32 s14, s21, 0xff
	s_cmp_eq_u32 s14, 0
	s_mov_b64 s[14:15], -1
	s_mov_b64 s[18:19], -1
	s_nop 0
	s_cbranch_scc0 .LBB0_1276
	global_load_dword v17, v16, s[78:79] offset:512 sc1
	s_waitcnt vmcnt(0)
	v_cmp_eq_u32_e32 vcc, 0, v17
	s_cbranch_vccnz .LBB0_1278
	s_mov_b64 s[18:19], 0

.LBB0_1290:
	s_and_b32 s20, s24, 0xff
	s_mov_b64 s[18:19], -1
	s_cmp_lg_u32 s20, 0
	s_mov_b64 s[22:23], -1
	s_nop 0
	s_cbranch_scc1 .LBB0_1293
	global_load_dword v2, v0, s[78:79] offset:512 sc1
	s_waitcnt vmcnt(0)
	v_cmp_eq_u32_e32 vcc, 0, v2
	s_cbranch_vccnz .LBB0_1295
	s_mov_b64 s[22:23], 0
	s_mov_b64 s[20:21], -1

.LBB0_1307:
	s_and_b32 s20, s26, 0xff
	s_cmp_lg_u32 s20, 0
	s_mov_b64 s[22:23], -1
	s_nop 0
	s_cbranch_scc1 .LBB0_1310
	global_load_dword v1, v0, s[12:13] sc1
	s_waitcnt vmcnt(0)
	v_cmp_eq_u32_e32 vcc, 0, v1
	s_cbranch_vccnz .LBB0_1312
	s_mov_b64 s[22:23], 0
	s_mov_b64 s[20:21], -1

.LBB0_2691:
	global_load_dword v15, v16, s[78:79] offset:1024 sc1
	s_waitcnt lgkmcnt(0)
	global_load_dword v0, v16, s[78:79] offset:1280 sc1
	global_load_dword v1, v16, s[78:79] offset:1536 sc1
	global_load_dword v2, v16, s[78:79] offset:1792 sc1
	global_load_dword v3, v16, s[78:79] offset:2048 sc1
	global_load_dword v4, v16, s[78:79] offset:2304 sc1
	global_load_dword v5, v16, s[78:79] offset:2560 sc1
	global_load_dword v6, v16, s[78:79] offset:2816 sc1
	global_load_dword v7, v16, s[78:79] offset:3072 sc1
	global_load_dword v8, v16, s[78:79] offset:3328 sc1
	global_load_dword v9, v16, s[78:79] offset:3584 sc1
	global_load_dword v10, v16, s[78:79] offset:3840 sc1
	global_load_dword v11, v16, s[4:5] sc1
	global_load_dword v12, v16, s[6:7] sc1
	global_load_dword v13, v16, s[10:11] sc1
	global_load_dword v14, v16, s[12:13] sc1
	s_mov_b64 s[14:15], -1
	s_mov_b64 s[16:17], -1
	s_waitcnt vmcnt(14)
	v_add_u32_e32 v17, v0, v15
	s_waitcnt vmcnt(13)
	v_add_u32_e32 v17, v17, v1
	s_waitcnt vmcnt(12)
	v_add_u32_e32 v17, v17, v2
	s_waitcnt vmcnt(11)
	v_add_u32_e32 v17, v17, v3
	s_waitcnt vmcnt(10)
	v_add_u32_e32 v17, v17, v4
	s_waitcnt vmcnt(9)
	v_add_u32_e32 v17, v17, v5
	s_waitcnt vmcnt(8)
	v_add_u32_e32 v17, v17, v6
	s_waitcnt vmcnt(7)
	v_add_u32_e32 v17, v17, v7
	s_waitcnt vmcnt(6)
	v_add_u32_e32 v17, v17, v8
	s_waitcnt vmcnt(5)
	v_add_u32_e32 v17, v17, v9
	s_waitcnt vmcnt(4)
	v_add_u32_e32 v17, v17, v10
	s_waitcnt vmcnt(3)
	v_add_u32_e32 v17, v17, v11
	s_waitcnt vmcnt(2)
	v_add_u32_e32 v17, v17, v12
	s_waitcnt vmcnt(1)
	v_add_u32_e32 v17, v17, v13
	s_waitcnt vmcnt(0)
	v_add_u32_e32 v17, v17, v14
	v_cmp_eq_u32_e32 vcc, s20, v17
	s_cbranch_vccnz .LBB0_2690
	s_and_b32 s14, s21, 0xff
	s_cmp_eq_u32 s14, 0
	s_mov_b64 s[14:15], -1
	s_mov_b64 s[18:19], -1
	s_nop 0
	s_cbranch_scc0 .LBB0_2695
	global_load_dword v17, v16, s[78:79] offset:512 sc1
	s_waitcnt vmcnt(0)
	v_cmp_eq_u32_e32 vcc, 0, v17
	s_cbranch_vccnz .LBB0_2697
	s_mov_b64 s[18:19], 0

.LBB0_2800:
	global_load_dword v15, v16, s[78:79] offset:1024 sc1
	s_waitcnt lgkmcnt(0)
	global_load_dword v0, v16, s[78:79] offset:1280 sc1
	global_load_dword v1, v16, s[78:79] offset:1536 sc1
	global_load_dword v2, v16, s[78:79] offset:1792 sc1
	global_load_dword v3, v16, s[78:79] offset:2048 sc1
	global_load_dword v4, v16, s[78:79] offset:2304 sc1
	global_load_dword v5, v16, s[78:79] offset:2560 sc1
	global_load_dword v6, v16, s[78:79] offset:2816 sc1
	global_load_dword v7, v16, s[78:79] offset:3072 sc1
	global_load_dword v8, v16, s[78:79] offset:3328 sc1
	global_load_dword v9, v16, s[78:79] offset:3584 sc1
	global_load_dword v10, v16, s[78:79] offset:3840 sc1
	global_load_dword v11, v16, s[2:3] sc1
	global_load_dword v12, v16, s[4:5] sc1
	global_load_dword v13, v16, s[6:7] sc1
	global_load_dword v14, v16, s[8:9] sc1
	s_mov_b64 s[10:11], -1
	s_mov_b64 s[12:13], -1
	s_waitcnt vmcnt(14)
	v_add_u32_e32 v17, v0, v15
	s_waitcnt vmcnt(13)
	v_add_u32_e32 v17, v17, v1
	s_waitcnt vmcnt(12)
	v_add_u32_e32 v17, v17, v2
	s_waitcnt vmcnt(11)
	v_add_u32_e32 v17, v17, v3
	s_waitcnt vmcnt(10)
	v_add_u32_e32 v17, v17, v4
	s_waitcnt vmcnt(9)
	v_add_u32_e32 v17, v17, v5
	s_waitcnt vmcnt(8)
	v_add_u32_e32 v17, v17, v6
	s_waitcnt vmcnt(7)
	v_add_u32_e32 v17, v17, v7
	s_waitcnt vmcnt(6)
	v_add_u32_e32 v17, v17, v8
	s_waitcnt vmcnt(5)
	v_add_u32_e32 v17, v17, v9
	s_waitcnt vmcnt(4)
	v_add_u32_e32 v17, v17, v10
	s_waitcnt vmcnt(3)
	v_add_u32_e32 v17, v17, v11
	s_waitcnt vmcnt(2)
	v_add_u32_e32 v17, v17, v12
	s_waitcnt vmcnt(1)
	v_add_u32_e32 v17, v17, v13
	s_waitcnt vmcnt(0)
	v_add_u32_e32 v17, v17, v14
	v_cmp_eq_u32_e32 vcc, s16, v17
	s_cbranch_vccnz .LBB0_2799
	s_and_b32 s10, s17, 0xff
	s_cmp_eq_u32 s10, 0
	s_mov_b64 s[10:11], -1
	s_mov_b64 s[14:15], -1
	s_nop 0
	s_cbranch_scc0 .LBB0_2804
	global_load_dword v17, v16, s[78:79] offset:512 sc1
	s_waitcnt vmcnt(0)
	v_cmp_eq_u32_e32 vcc, 0, v17
	s_cbranch_vccnz .LBB0_2806
	s_mov_b64 s[14:15], 0

.LBB0_2818:
	s_and_b32 s16, s20, 0xff
	s_mov_b64 s[14:15], -1
	s_cmp_lg_u32 s16, 0
	s_mov_b64 s[18:19], -1
	s_nop 0
	s_cbranch_scc1 .LBB0_2821
	global_load_dword v2, v0, s[78:79] offset:512 sc1
	s_waitcnt vmcnt(0)
	v_cmp_eq_u32_e32 vcc, 0, v2
	s_cbranch_vccnz .LBB0_2823
	s_mov_b64 s[18:19], 0
	s_mov_b64 s[16:17], -1

.LBB0_2835:
	s_and_b32 s16, s22, 0xff
	s_cmp_lg_u32 s16, 0
	s_mov_b64 s[18:19], -1
	s_nop 0
	s_cbranch_scc1 .LBB0_2838
	global_load_dword v1, v0, s[8:9] sc1
	s_waitcnt vmcnt(0)
	v_cmp_eq_u32_e32 vcc, 0, v1
	s_cbranch_vccnz .LBB0_2840
	s_mov_b64 s[18:19], 0
	s_mov_b64 s[16:17], -1
